# layer-0 attention tile loop: the tile-rotation register copies and their vmcnt waits moved from mid-iteration to the end of the iteration (loads get the whole iteration to land) (on v101)
# speedup vs baseline: 1.0008x; 1.0008x over previous
.LBB0_477:
	s_lshl_b32 s5, s5, 5
	s_sub_i32 s8, s5, 64
	v_add_u32_e32 v82, s8, v139
	v_add_u32_e32 v86, s8, v138
	v_add_u32_e32 v90, s8, v137
	v_add_u32_e32 v94, s8, v111
	s_ashr_i32 s9, s8, 31
	v_ashrrev_i32_e32 v83, 31, v82
	v_ashrrev_i32_e32 v87, 31, v86
	v_ashrrev_i32_e32 v91, 31, v90
	v_ashrrev_i32_e32 v95, 31, v94
	s_lshl_b64 s[16:17], s[8:9], 1
	v_lshlrev_b64 v[82:83], 13, v[82:83]
	v_lshlrev_b64 v[86:87], 13, v[86:87]
	v_lshlrev_b64 v[90:91], 13, v[90:91]
	v_lshlrev_b64 v[94:95], 13, v[94:95]
	v_lshl_add_u64 v[66:67], v[128:129], 0, s[16:17]
	v_lshl_add_u64 v[70:71], v[130:131], 0, s[16:17]
	v_lshl_add_u64 v[74:75], v[132:133], 0, s[16:17]
	v_lshl_add_u64 v[78:79], v[134:135], 0, s[16:17]
	v_lshl_add_u64 v[82:83], v[124:125], 0, v[82:83]
	v_lshl_add_u64 v[86:87], v[120:121], 0, v[86:87]
	v_lshl_add_u64 v[90:91], v[122:123], 0, v[90:91]
	v_lshl_add_u64 v[94:95], v[120:121], 0, v[94:95]
	global_load_dwordx4 v[66:69], v[66:67], off
	s_add_i32 s8, s46, -1
	global_load_dwordx4 v[70:73], v[70:71], off
	s_max_u32 s5, s8, 2
	global_load_dwordx4 v[74:77], v[74:75], off
	s_nop 0
	global_load_dwordx4 v[78:81], v[78:79], off
	s_nop 0
	global_load_dwordx4 v[82:85], v[82:83], off
	s_nop 0
	global_load_dwordx4 v[86:89], v[86:87], off
	s_nop 0
	global_load_dwordx4 v[90:93], v[90:91], off
	s_nop 0
	global_load_dwordx4 v[94:97], v[94:95], off
	s_waitcnt vmcnt(15)
	ds_write_b128 v140, v[34:37]
	s_waitcnt vmcnt(14)
	ds_write_b128 v140, v[38:41] offset:1024
	s_waitcnt vmcnt(13)
	ds_write_b128 v140, v[42:45] offset:2048
	s_waitcnt vmcnt(12)
	ds_write_b128 v140, v[46:49] offset:3072
	s_waitcnt vmcnt(11)
	ds_write_b128 v141, v[98:101] offset:4096
	s_waitcnt vmcnt(10)
	ds_write_b128 v141, v[102:105] offset:5120
	s_waitcnt vmcnt(9)
	ds_write_b128 v141, v[106:109] offset:6144
	s_waitcnt vmcnt(8)
	ds_write_b128 v141, v[116:119] offset:7168
	ds_read_b128 v[34:37], v144
	ds_read_b128 v[98:101], v145
	s_waitcnt lgkmcnt(1)
	v_mfma_f32_32x32x16_bf16 v[34:49], v[34:37], v[50:53], 0
	s_waitcnt lgkmcnt(0)
	v_mfma_f32_32x32x16_bf16 v[34:49], v[98:101], v[54:57], v[34:49]
	ds_read_b128 v[98:101], v146
	s_waitcnt lgkmcnt(0)
	v_mfma_f32_32x32x16_bf16 v[34:49], v[98:101], v[58:61], v[34:49]
	ds_read_b128 v[98:101], v147
	s_waitcnt lgkmcnt(0)
	v_mfma_f32_32x32x16_bf16 v[34:49], v[98:101], v[62:65], v[34:49]
	s_nop 11
	v_mul_f32_e32 v1, 0x3e38aa3b, v34
	v_exp_f32_e64 v34, -|v1|
	v_min_f32_e32 v98, 0, v1
	v_min_f32_e64 v1, -v1, 0
	v_add_f32_e32 v34, 1.0, v34
	v_log_f32_e32 v34, v34
	s_nop 0
	v_sub_f32_e32 v100, v98, v34
	v_sub_f32_e32 v1, v1, v34
	v_mul_f32_e32 v34, 0x3e38aa3b, v35
	v_exp_f32_e64 v35, -|v34|
	v_min_f32_e32 v98, 0, v34
	v_min_f32_e64 v34, -v34, 0
	v_add_f32_e32 v35, 1.0, v35
	v_log_f32_e32 v35, v35
	s_nop 0
	v_sub_f32_e32 v101, v98, v35
	v_sub_f32_e32 v34, v34, v35
	v_mul_f32_e32 v35, 0x3e38aa3b, v36
	v_exp_f32_e64 v36, -|v35|
	v_min_f32_e32 v98, 0, v35
	v_min_f32_e64 v35, -v35, 0
	v_add_f32_e32 v36, 1.0, v36
	v_log_f32_e32 v36, v36
	s_nop 0
	v_sub_f32_e32 v102, v98, v36
	v_sub_f32_e32 v35, v35, v36
	v_mul_f32_e32 v36, 0x3e38aa3b, v37
	v_exp_f32_e64 v37, -|v36|
	v_min_f32_e32 v98, 0, v36
	v_min_f32_e64 v36, -v36, 0
	v_add_f32_e32 v37, 1.0, v37
	v_log_f32_e32 v37, v37
	s_nop 0
	v_sub_f32_e32 v103, v98, v37
	v_sub_f32_e32 v36, v36, v37
	v_mul_f32_e32 v37, 0x3e38aa3b, v38
	v_exp_f32_e64 v38, -|v37|
	v_min_f32_e32 v98, 0, v37
	v_min_f32_e64 v37, -v37, 0
	v_add_f32_e32 v38, 1.0, v38
	v_log_f32_e32 v38, v38
	s_nop 0
	v_sub_f32_e32 v104, v98, v38
	v_sub_f32_e32 v37, v37, v38
	v_mul_f32_e32 v38, 0x3e38aa3b, v39
	v_exp_f32_e64 v39, -|v38|
	v_min_f32_e32 v98, 0, v38
	v_min_f32_e64 v38, -v38, 0
	v_add_f32_e32 v39, 1.0, v39
	v_log_f32_e32 v39, v39
	s_nop 0
	v_sub_f32_e32 v105, v98, v39
	v_sub_f32_e32 v38, v38, v39
	v_mul_f32_e32 v39, 0x3e38aa3b, v40
	v_exp_f32_e64 v40, -|v39|
	v_min_f32_e32 v98, 0, v39
	v_min_f32_e64 v39, -v39, 0
	v_add_f32_e32 v40, 1.0, v40
	v_log_f32_e32 v40, v40
	s_nop 0
	v_sub_f32_e32 v106, v98, v40
	v_sub_f32_e32 v39, v39, v40
	v_mul_f32_e32 v40, 0x3e38aa3b, v41
	v_exp_f32_e64 v41, -|v40|
	v_min_f32_e32 v98, 0, v40
	v_min_f32_e64 v40, -v40, 0
	v_add_f32_e32 v41, 1.0, v41
	v_log_f32_e32 v41, v41
	s_nop 0
	v_sub_f32_e32 v98, v98, v41
	v_sub_f32_e32 v40, v40, v41
	v_mul_f32_e32 v41, 0x3e38aa3b, v42
	v_exp_f32_e64 v42, -|v41|
	v_min_f32_e32 v99, 0, v41
	v_min_f32_e64 v41, -v41, 0
	v_add_f32_e32 v42, 1.0, v42
	v_log_f32_e32 v42, v42
	s_nop 0
	v_sub_f32_e32 v107, v99, v42
	v_sub_f32_e32 v41, v41, v42
	v_mul_f32_e32 v42, 0x3e38aa3b, v43
	v_exp_f32_e64 v43, -|v42|
	v_min_f32_e32 v99, 0, v42
	v_min_f32_e64 v42, -v42, 0
	v_add_f32_e32 v43, 1.0, v43
	v_log_f32_e32 v43, v43
	s_nop 0
	v_sub_f32_e32 v108, v99, v43
	v_sub_f32_e32 v42, v42, v43
	v_mul_f32_e32 v43, 0x3e38aa3b, v44
	v_exp_f32_e64 v44, -|v43|
	v_min_f32_e32 v99, 0, v43
	v_min_f32_e64 v43, -v43, 0
	v_add_f32_e32 v44, 1.0, v44
	v_log_f32_e32 v44, v44
	s_nop 0
	v_sub_f32_e32 v109, v99, v44
	v_sub_f32_e32 v43, v43, v44
	v_mul_f32_e32 v44, 0x3e38aa3b, v45
	v_exp_f32_e64 v45, -|v44|
	v_min_f32_e32 v99, 0, v44
	v_min_f32_e64 v44, -v44, 0
	v_add_f32_e32 v45, 1.0, v45
	v_log_f32_e32 v45, v45
	s_nop 0
	v_sub_f32_e32 v116, v99, v45
	v_sub_f32_e32 v44, v44, v45
	v_mul_f32_e32 v45, 0x3e38aa3b, v46
	v_exp_f32_e64 v46, -|v45|
	v_min_f32_e32 v99, 0, v45
	v_min_f32_e64 v45, -v45, 0
	v_add_f32_e32 v46, 1.0, v46
	v_log_f32_e32 v46, v46
	s_nop 0
	v_sub_f32_e32 v117, v99, v46
	v_sub_f32_e32 v45, v45, v46
	v_mul_f32_e32 v46, 0x3e38aa3b, v47
	v_exp_f32_e64 v47, -|v46|
	v_min_f32_e32 v99, 0, v46
	v_min_f32_e64 v46, -v46, 0
	v_add_f32_e32 v47, 1.0, v47
	v_log_f32_e32 v47, v47
	s_nop 0
	v_sub_f32_e32 v118, v99, v47
	v_sub_f32_e32 v46, v46, v47
	v_mul_f32_e32 v47, 0x3e38aa3b, v48
	v_exp_f32_e64 v48, -|v47|
	v_min_f32_e32 v99, 0, v47
	v_min_f32_e64 v47, -v47, 0
	v_add_f32_e32 v48, 1.0, v48
	v_log_f32_e32 v48, v48
	s_nop 0
	v_sub_f32_e32 v119, v99, v48
	v_sub_f32_e32 v47, v47, v48
	v_mul_f32_e32 v48, 0x3e38aa3b, v49
	v_exp_f32_e64 v99, -|v48|
	v_min_f32_e64 v49, -v48, 0
	v_min_f32_e32 v48, 0, v48
	v_add_f32_e32 v99, 1.0, v99
	v_log_f32_e32 v99, v99
	s_nop 0
	v_sub_f32_e32 v49, v49, v99
	v_sub_f32_e32 v127, v48, v99
	v_add_f32_e32 v48, 0, v40
	v_add_f32_e32 v49, 0, v49
	v_add_f32_e32 v39, v39, v48
	v_add_f32_e32 v47, v47, v49
	v_add_f32_e32 v148, v38, v39
	v_add_f32_e32 v46, v46, v47
	v_add_f32_e32 v149, v37, v148
	v_add_f32_e32 v45, v45, v46
	v_add_f32_e32 v150, v36, v149
	v_add_f32_e32 v44, v44, v45
	v_add_f32_e32 v151, v35, v150
	v_add_f32_e32 v43, v43, v44
	v_add_f32_e32 v40, v34, v151
	v_add_f32_e32 v42, v42, v43
	v_add_f32_e32 v35, v1, v40
	v_add_f32_e32 v37, v41, v42
	ds_bpermute_b32 v34, v142, v35
	ds_bpermute_b32 v36, v142, v37
	v_add_f32_e32 v1, v126, v37
	v_add_f32_e32 v100, v100, v40
	v_add_f32_e32 v40, v107, v42
	v_add_f32_e32 v41, v108, v43
	s_waitcnt lgkmcnt(0)
	v_add_f32_e32 v99, v1, v36
	v_cndmask_b32_e64 v1, 0, v34, s[40:41]
	v_add_f32_e32 v107, v102, v150
	v_add_f32_e32 v108, v103, v149
	v_add_f32_e32 v39, v105, v39
	v_pk_add_f32 v[102:103], v[0:1], v[98:99]
	v_add_f32_e32 v105, v106, v48
	v_add_f32_e32 v39, v39, v103
	v_exp_f32_e32 v99, v39
	v_add_f32_e32 v39, v105, v103
	v_add_f32_e32 v101, v101, v151
	v_add_f32_e32 v1, v100, v103
	v_exp_f32_e32 v100, v39
	v_add_f32_e32 v39, v102, v103
	v_cndmask_b32_e64 v38, 0, v36, s[40:41]
	v_add_f32_e32 v43, v116, v45
	v_add_f32_e32 v45, v118, v47
	v_add_f32_e32 v47, v101, v103
	v_exp_f32_e32 v101, v39
	v_mov_b32_e32 v39, v0
	v_pk_add_f32 v[38:39], v[126:127], v[38:39]
	v_add_f32_e32 v42, v109, v44
	v_add_f32_e32 v40, v38, v40
	v_add_f32_e32 v104, v104, v148
	v_exp_f32_e32 v102, v40
	v_add_f32_e32 v40, v38, v41
	v_add_f32_e32 v44, v117, v46
	v_add_f32_e32 v46, v119, v49
	v_add_f32_e32 v48, v107, v103
	v_add_f32_e32 v49, v108, v103
	v_add_f32_e32 v98, v104, v103
	v_exp_f32_e32 v103, v40
	v_add_f32_e32 v40, v38, v42
	v_exp_f32_e32 v104, v40
	v_add_f32_e32 v40, v38, v43
	v_exp_f32_e32 v43, v40
	v_add_f32_e32 v40, v38, v44
	v_exp_f32_e32 v44, v40
	v_add_f32_e32 v40, v38, v45
	v_exp_f32_e32 v45, v40
	v_add_f32_e32 v40, v38, v46
	v_add_f32_e32 v38, v38, v39
	v_exp_f32_e32 v1, v1
	v_exp_f32_e32 v47, v47
	v_exp_f32_e32 v48, v48
	v_exp_f32_e32 v49, v49
	v_exp_f32_e32 v46, v40
	v_exp_f32_e32 v105, v38
	v_cvt_pk_bf16_f32 v38, v1, v47
	v_cvt_pk_bf16_f32 v39, v48, v49
	v_cvt_pk_bf16_f32 v44, v44, v45
	v_cvt_pk_bf16_f32 v45, v46, v105
	ds_read_b128 v[46:49], v143 offset:4096
	v_exp_f32_e32 v98, v98
	v_cvt_pk_bf16_f32 v41, v100, v101
	v_cvt_pk_bf16_f32 v42, v102, v103
	v_cvt_pk_bf16_f32 v43, v104, v43
	v_cvt_pk_bf16_f32 v40, v98, v99
	v_pk_add_f32 v[34:35], v[34:35], v[36:37]
	s_waitcnt lgkmcnt(0)
	v_mfma_f32_32x32x16_bf16 v[2:17], v[46:49], v[38:41], v[2:17]
	ds_read_b128 v[46:49], v136 offset:4096
	v_add_f32_e32 v1, v34, v35
	v_add_f32_e32 v126, v126, v1
	v_cmp_gt_f32_e32 vcc, s53, v126
	s_cmp_lg_u64 vcc, exec
	s_cselect_b64 s[16:17], -1, 0
	s_cmp_gt_u32 s46, 1
	s_waitcnt lgkmcnt(0)
	v_mfma_f32_32x32x16_bf16 v[2:17], v[46:49], v[42:45], v[2:17]
	ds_read_b128 v[46:49], v143 offset:6144
	s_cselect_b64 s[42:43], -1, 0
	s_and_b64 s[16:17], s[16:17], s[42:43]
	s_waitcnt lgkmcnt(0)
	v_mfma_f32_32x32x16_bf16 v[18:33], v[46:49], v[38:41], v[18:33]
	ds_read_b128 v[38:41], v136 offset:6144
	s_and_b64 vcc, exec, s[16:17]
	s_mov_b32 s46, s8
	s_waitcnt lgkmcnt(0)
	v_mfma_f32_32x32x16_bf16 v[18:33], v[38:41], v[42:45], v[18:33]
	s_waitcnt vmcnt(0)
	v_mov_b64_e32 v[100:101], v[80:81]
	v_mov_b64_e32 v[34:35], v[94:95]
	v_mov_b64_e32 v[104:105], v[76:77]
	v_mov_b64_e32 v[108:109], v[72:73]
	v_mov_b64_e32 v[118:119], v[68:69]
	v_mov_b64_e32 v[46:47], v[82:83]
	v_mov_b64_e32 v[36:37], v[96:97]
	v_mov_b64_e32 v[48:49], v[84:85]
	v_mov_b64_e32 v[98:99], v[78:79]
	v_mov_b64_e32 v[38:39], v[90:91]
	v_mov_b64_e32 v[42:43], v[86:87]
	v_mov_b64_e32 v[40:41], v[92:93]
	v_mov_b64_e32 v[44:45], v[88:89]
	v_mov_b64_e32 v[102:103], v[74:75]
	v_mov_b64_e32 v[106:107], v[70:71]
	v_mov_b64_e32 v[116:117], v[66:67]
	s_cbranch_vccnz .LBB0_477
